# plus: forget-gate cumsum moved to workgroups with only one Q up-projection tile; loop-exit barriers of the hand-written attention loops removed
# baseline (speedup 1.0000x reference)
.LBB0_211:
	v_writelane_b32 v253, s55, 6
	v_writelane_b32 v253, s54, 7
	v_writelane_b32 v253, s56, 8
	s_nop 1
	v_writelane_b32 v253, s57, 9
	v_writelane_b32 v253, s58, 10
	v_writelane_b32 v253, s59, 11
	v_writelane_b32 v253, s60, 12
	v_writelane_b32 v253, s61, 13
	v_writelane_b32 v253, s62, 14
	v_writelane_b32 v253, s63, 15
	v_writelane_b32 v253, s64, 16
	v_writelane_b32 v253, s65, 17
	v_writelane_b32 v253, s66, 18
	v_writelane_b32 v253, s67, 19
	v_writelane_b32 v253, s68, 20
	v_writelane_b32 v253, s69, 21
	v_writelane_b32 v253, s70, 22
	v_writelane_b32 v253, s71, 23
	s_or_b64 exec, exec, s[0:1]
	s_add_u32 s78, s22, 0x2600000
	s_addc_u32 s79, s23, 0
	s_add_u32 s80, s22, 0x2800000
	s_addc_u32 s81, s23, 0
	s_add_u32 s82, s22, 0x200
	s_addc_u32 s83, s23, 0
	s_add_u32 s86, s22, 0x1000
	s_addc_u32 s87, s23, 0
	s_add_u32 s84, s22, 0x1100
	s_addc_u32 s85, s23, 0
	s_add_u32 s0, s22, 0x1200
	s_addc_u32 s1, s23, 0
	v_writelane_b32 v253, s0, 24
	s_movk_i32 s4, 0xc1
	s_mov_b32 s97, 0
	v_writelane_b32 v253, s1, 25
	s_add_u32 s0, s22, 0x1300
	s_addc_u32 s1, s23, 0
	v_writelane_b32 v253, s0, 26
	v_mov_b32_e32 v13, 0
	v_mov_b32_e32 v221, 0x1000
	v_writelane_b32 v253, s1, 27
	s_add_u32 s0, s22, 0x3400
	s_addc_u32 s1, s23, 0
	v_writelane_b32 v253, s0, 28
	v_mov_b32_e32 v252, 0x2000
	v_mov_b32_e32 v166, 0x358637bd
	v_writelane_b32 v253, s1, 29
	s_add_u32 s0, s22, 0x3500
	s_addc_u32 s1, s23, 0
	v_writelane_b32 v253, s0, 30
	s_cmp_eq_u32 s28, 0
	v_mov_b32_e32 v167, 0x7f800000
	v_writelane_b32 v253, s1, 31
	s_cselect_b64 s[0:1], -1, 0
	v_writelane_b32 v253, s0, 32
	v_mov_b32_e32 v220, 0xff800000
	s_movk_i32 s92, 0x600
	v_writelane_b32 v253, s1, 33
	s_add_u32 s0, s22, 0x2f00000
	s_addc_u32 s1, s23, 0
	s_add_u32 s70, s22, 0x3000000
	s_addc_u32 s71, s23, 0
	s_lshl_b32 s10, s24, 7
	v_writelane_b32 v253, s0, 34
	s_cmpk_lt_i32 s28, 0x600
	s_mov_b32 s29, 0x800000
	v_writelane_b32 v253, s1, 35
	s_cselect_b64 s[0:1], -1, 0
	v_writelane_b32 v253, s0, 36
	s_ashr_i32 s12, s28, 31
	s_mov_b64 s[48:49], 0x200
	v_writelane_b32 v253, s1, 37
	s_lshr_b32 s0, s12, 29
	s_add_i32 s0, s28, s0
	s_ashr_i32 s1, s0, 3
	s_and_b32 s0, s0, -8
	s_sub_i32 s0, s28, s0
	s_add_u32 s50, s22, 0x7000000
	s_addc_u32 s51, s23, 0
	s_add_u32 s2, s22, 0xd000000
	s_addc_u32 s3, s23, 0
	s_add_u32 s44, s22, 0x11000000
	s_addc_u32 s45, s23, 0
	s_add_u32 s14, s22, 0x12000000
	v_writelane_b32 v253, s2, 38
	s_addc_u32 s15, s23, 0
	s_mov_b64 s[36:37], 0x800
	v_writelane_b32 v253, s3, 39
	s_add_u32 s2, s22, 0x12800000
	s_addc_u32 s3, s23, 0
	v_writelane_b32 v253, s2, 40
	s_mov_b64 s[42:43], 0x80
	s_mov_b64 s[68:69], 0x2000
	v_writelane_b32 v253, s3, 41
	s_add_u32 s2, s22, 0x2a00000
	s_addc_u32 s3, s23, 0
	s_add_u32 s88, s22, 0x2d00000
	s_addc_u32 s89, s23, 0
	s_add_u32 s90, s22, 0x2c00000
	v_writelane_b32 v253, s2, 42
	s_addc_u32 s91, s23, 0
	s_ashr_i32 s93, s24, 31
	v_writelane_b32 v253, s3, 43
	s_add_u32 s2, s22, 0x2b00000
	s_addc_u32 s3, s23, 0
	v_writelane_b32 v253, s2, 44
	s_add_i32 s46, s28, 0xffffff80
	s_cmp_lt_u32 s46, 64
	s_mov_b64 s[46:47], 0x20000
	v_writelane_b32 v253, s3, 45
	s_cselect_b64 s[2:3], -1, 0
	v_writelane_b32 v253, s2, 46
	s_cmpk_lt_i32 s28, 0x180
	s_barrier
	v_writelane_b32 v253, s3, 47
	s_cselect_b64 s[2:3], -1, 0
	v_writelane_b32 v253, s2, 48
	s_nop 1
	v_writelane_b32 v253, s3, 49
	s_add_u32 s2, s22, 0x12a00000
	s_addc_u32 s3, s23, 0
	v_writelane_b32 v253, s2, 50
	s_cmpk_lt_i32 s28, 0x200
	s_nop 0
	v_writelane_b32 v253, s3, 51
	s_cselect_b64 s[2:3], -1, 0
	v_writelane_b32 v253, s2, 52
	s_nop 1
	v_writelane_b32 v253, s3, 53
	s_lshl_b32 s2, s0, 6
	s_add_u32 s3, s22, 0x15a00000
	v_writelane_b32 v253, s3, 54
	s_addc_u32 s3, s23, 0
	v_writelane_b32 v253, s3, 55
	s_add_u32 s3, s22, 0x36b0
	v_writelane_b32 v253, s3, 56
	s_addc_u32 s3, s23, 0
	v_writelane_b32 v253, s3, 57
	s_add_u32 s3, s22, 0xb000000
	v_writelane_b32 v253, s3, 58
	s_addc_u32 s3, s23, 0
	v_writelane_b32 v253, s3, 59
	s_add_u32 s3, s22, 0x9000000
	v_writelane_b32 v253, s3, 60
	s_addc_u32 s3, s23, 0
	v_writelane_b32 v253, s3, 61
	s_add_u32 s3, s22, 0x17a00000
	v_writelane_b32 v253, s3, 62
	s_addc_u32 s3, s23, 0
	s_cmp_lt_i32 s0, 0
	s_cselect_b32 s4, s4, 0xc0
	v_writelane_b32 v253, s3, 63
	s_mul_i32 s3, s0, 0x41
	s_mul_i32 s4, s0, s4
	s_cselect_b32 s5, 49, 48
	s_cselect_b32 s2, s3, s2
	s_add_i32 s4, s4, s1
	s_mul_hi_i32 s3, s4, 0x2aaaaaab
	s_lshr_b32 s6, s3, 31
	s_ashr_i32 s3, s3, 4
	s_add_i32 s3, s3, s6
	s_mul_i32 s6, s3, 0x60
	s_sub_i32 s4, s4, s6
	s_bfe_i32 s6, s4, 0x80000
	s_bfe_u32 s6, s6, 0x3000c
	s_mul_i32 s0, s0, s5
	s_add_i32 s6, s4, s6
	s_add_i32 s0, s0, s1
	s_and_b32 s7, s6, 0xf8
	s_mul_hi_i32 s5, s0, 0x2aaaaaab
	s_sub_i32 s4, s4, s7
	s_lshr_b32 s7, s5, 31
	s_ashr_i32 s5, s5, 2
	s_add_i32 s5, s5, s7
	s_mul_i32 s7, s5, 24
	s_sub_i32 s0, s0, s7
	s_bfe_i32 s7, s0, 0x80000
	s_add_i32 s1, s2, s1
	s_bfe_u32 s7, s7, 0x3000c
	s_ashr_i32 s2, s1, 31
	s_add_i32 s7, s0, s7
	s_lshr_b32 s2, s2, 27
	s_and_b32 s8, s7, 0xf8
	s_add_i32 s2, s1, s2
	s_sub_i32 s0, s0, s8
	s_and_b32 s8, s2, 0xffe0
	s_sub_i32 s1, s1, s8
	s_bfe_i32 s8, s1, 0x80000
	s_bfe_u32 s8, s8, 0x3000c
	s_add_i32 s8, s1, s8
	s_lshl_b32 s3, s3, 3
	s_sext_i32_i8 s4, s4
	s_and_b32 s9, s8, 0xf8
	s_add_i32 s16, s3, s4
	s_lshl_b32 s3, s5, 3
	s_sext_i32_i8 s0, s0
	s_sub_i32 s1, s1, s9
	s_add_i32 s26, s3, s0
	s_ashr_i32 s0, s2, 5
	s_bfe_i32 s2, s8, 0x80000
	s_bfe_i32 s6, s6, 0x80000
	s_lshl_b32 s0, s0, 3
	s_sext_i32_i16 s2, s2
	s_sext_i32_i8 s1, s1
	s_sext_i32_i16 s6, s6
	s_bfe_i32 s4, s7, 0x80000
	s_add_i32 s8, s0, s1
	s_ashr_i32 s0, s2, 3
	s_sext_i32_i16 s4, s4
	v_writelane_b32 v254, s0, 0
	s_lshr_b32 s0, s2, 3
	s_ashr_i32 s2, s6, 3
	s_bfe_i64 s[0:1], s[0:1], 0x100000
	v_writelane_b32 v254, s2, 1
	s_ashr_i32 s3, s4, 3
	v_writelane_b32 v254, s3, 2
	s_lshl_b64 s[30:31], s[0:1], 16
	s_ashr_i32 s9, s8, 31
	v_writelane_b32 v254, s30, 3
	s_lshr_b32 s2, s6, 3
	s_lshr_b32 s4, s4, 3
	s_lshl_b64 s[6:7], s[8:9], 16
	v_writelane_b32 v254, s31, 4
	s_add_u32 s6, s14, s6
	v_writelane_b32 v254, s14, 5
	s_addc_u32 s7, s15, s7
	s_nop 0
	v_writelane_b32 v254, s15, 6
	s_add_u32 s14, s6, 0x8000
	v_writelane_b32 v254, s6, 7
	s_addc_u32 s15, s7, 0
	s_lshl_b64 s[0:1], s[0:1], 19
	v_writelane_b32 v254, s7, 8
	v_writelane_b32 v254, s14, 9
	s_nop 1
	v_writelane_b32 v254, s15, 10
	v_writelane_b32 v254, s0, 11
	s_nop 1
	v_writelane_b32 v254, s1, 12
	s_mov_b32 s0, s8
	v_writelane_b32 v254, s0, 13
	s_nop 1
	v_writelane_b32 v254, s1, 14
	s_lshl_b64 s[0:1], s[8:9], 19
	s_add_u32 s0, s70, s0
	s_addc_u32 s1, s71, s1
	s_add_u32 s6, s0, 0x40000
	v_writelane_b32 v254, s0, 15
	s_addc_u32 s7, s1, 0
	s_ashr_i32 s17, s16, 31
	v_writelane_b32 v254, s1, 16
	v_writelane_b32 v254, s6, 17
	s_bfe_i64 s[0:1], s[2:3], 0x100000
	s_lshl_b64 s[0:1], s[0:1], 19
	v_writelane_b32 v254, s7, 18
	v_writelane_b32 v254, s0, 19
	s_nop 1
	v_writelane_b32 v254, s1, 20
	s_mov_b32 s0, s16
	v_writelane_b32 v254, s0, 21
	s_nop 1
	v_writelane_b32 v254, s1, 22
	s_lshl_b64 s[0:1], s[16:17], 19
	s_add_u32 s0, s70, s0
	s_addc_u32 s1, s71, s1
	s_add_u32 s2, s0, 0x40000
	v_writelane_b32 v254, s0, 23
	s_addc_u32 s3, s1, 0
	s_ashr_i32 s27, s26, 31
	v_writelane_b32 v254, s1, 24
	v_writelane_b32 v254, s2, 25
	s_bfe_i64 s[0:1], s[4:5], 0x100000
	s_lshl_b64 s[0:1], s[0:1], 17
	v_writelane_b32 v254, s3, 26
	v_writelane_b32 v254, s0, 27
	s_nop 1
	v_writelane_b32 v254, s1, 28
	s_mov_b32 s0, s26
	v_writelane_b32 v254, s0, 29
	s_nop 1
	v_writelane_b32 v254, s1, 30
	s_lshl_b64 s[0:1], s[26:27], 17
	s_add_u32 s2, s44, s0
	s_mul_i32 s0, s25, s24
	s_mul_i32 s0, s0, s53
	s_addc_u32 s3, s45, s1
	v_writelane_b32 v254, s0, 31
	s_add_u32 s0, s2, 0x10000
	v_writelane_b32 v254, s2, 32
	s_addc_u32 s1, s3, 0
	s_nop 0
	v_writelane_b32 v254, s3, 33
	v_writelane_b32 v254, s0, 34
	s_nop 1
	v_writelane_b32 v254, s1, 35
	s_add_u32 s0, s22, 0x3000400
	v_writelane_b32 v254, s0, 36
	s_addc_u32 s0, s23, 0
	s_ashr_i32 s11, s10, 31
	v_writelane_b32 v254, s0, 37
	s_lshl_b64 s[0:1], s[10:11], 11
	v_writelane_b32 v254, s0, 38
	s_lshl_b64 s[94:95], s[10:11], 12
	s_nop 0
	v_writelane_b32 v254, s1, 39
	s_mov_b32 s0, s10
	v_writelane_b32 v254, s0, 40
	s_nop 1
	v_writelane_b32 v254, s1, 41
	s_add_u32 s0, s24, s28
	v_writelane_b32 v254, s12, 42
	s_addc_u32 s1, s93, s12
	v_writelane_b32 v254, s0, 43
	s_nop 1
	v_writelane_b32 v254, s1, 44
	s_add_u32 s0, s22, 0xb020000
	v_writelane_b32 v254, s0, 45
	s_addc_u32 s0, s23, 0
	v_writelane_b32 v254, s0, 46
	s_add_u32 s0, s22, 0x2b00200
	v_writelane_b32 v254, s0, 47
	s_addc_u32 s0, s23, 0
	v_writelane_b32 v254, s0, 48
	s_add_u32 s0, s22, 0x9020000
	v_writelane_b32 v254, s0, 49
	s_addc_u32 s0, s23, 0
	v_writelane_b32 v254, s0, 50
	s_add_i32 s0, 0, 0x20000
	v_writelane_b32 v254, s0, 51
	s_add_i32 s0, 0, 0x20004
	v_writelane_b32 v254, s0, 52
	s_mov_b32 s0, s97
	v_writelane_b32 v254, s0, 53
	s_add_i32 s2, 0, 0x20040
	s_nop 0
	v_writelane_b32 v254, s1, 54
	v_writelane_b32 v254, s84, 55
	s_nop 1
	v_writelane_b32 v254, s85, 56
	v_writelane_b32 v254, s28, 57
	v_writelane_b32 v254, s82, 58
	s_nop 1
	v_writelane_b32 v254, s83, 59
	s_branch .LBB0_215

.LBB0_503:
	s_or_b64 exec, exec, s[0:1]
	s_mov_b32 s0, s33
	s_waitcnt lgkmcnt(0)
	s_barrier
	v_mbcnt_lo_u32_b32 v12, -1, 0
	v_mbcnt_hi_u32_b32 v12, -1, v12
	s_nop 0
	v_lshl_or_b32 v0, s0, 6, v12
	v_readlane_b32 s0, v253, 46
	v_readlane_b32 s1, v253, 47
	s_andn2_b64 vcc, exec, s[0:1]
	v_readfirstlane_b32 s0, v0
	s_cbranch_vccnz .LBB0_512
	s_ashr_i32 s3, s0, 6
	v_lshlrev_b32_e32 v20, 2, v12
	s_lshl_b32 s4, s3, 2
	v_add_u32_e32 v21, 0xf8, v20
	v_lshlrev_b32_e32 v18, 3, v0
	s_add_i32 s25, s4, 0
	v_readlane_b32 s4, v253, 44
	v_and_b32_e32 v28, 0xfc, v21
	v_add_u32_e32 v21, 0xf0, v20
	v_and_b32_e32 v2, 63, v12
	v_ashrrev_i32_e32 v19, 31, v18
	v_readlane_b32 s5, v253, 45
	v_and_b32_e32 v29, 0xfc, v21
	v_add_u32_e32 v21, 0xe0, v20
	v_cmp_eq_u32_e64 s[0:1], 63, v2
	v_lshl_add_u64 v[0:1], v[18:19], 2, s[4:5]
	v_cmp_gt_u32_e64 s[14:15], 32, v2
	v_cmp_gt_u32_e64 s[4:5], 16, v2
	v_cmp_gt_u32_e64 s[6:7], 8, v2
	v_cmp_gt_u32_e64 s[8:9], 4, v2
	v_cmp_gt_u32_e64 s[10:11], 2, v2
	v_cmp_eq_u32_e64 s[12:13], 0, v2
	v_lshlrev_b64 v[2:3], 5, v[18:19]
	v_or_b32_e32 v4, 1, v18
	v_or_b32_e32 v6, 2, v18
	v_or_b32_e32 v8, 3, v18
	v_or_b32_e32 v10, 4, v18
	v_or_b32_e32 v14, 5, v18
	v_or_b32_e32 v16, 6, v18
	v_or_b32_e32 v18, 7, v18
	v_and_b32_e32 v30, 0xfc, v21
	v_add_u32_e32 v21, 0xc0, v20
	s_cmp_gt_i32 s3, 0
	v_ashrrev_i32_e32 v5, 31, v4
	v_ashrrev_i32_e32 v7, 31, v6
	v_ashrrev_i32_e32 v9, 31, v8
	v_ashrrev_i32_e32 v11, 31, v10
	v_ashrrev_i32_e32 v15, 31, v14
	v_ashrrev_i32_e32 v17, 31, v16
	v_ashrrev_i32_e32 v19, 31, v18
	v_add_u32_e32 v12, 0xfc, v20
	v_and_b32_e32 v31, 0xfc, v21
	s_movk_i32 s16, 0x80
	v_bfrev_b32_e32 v21, 0.5
	s_cselect_b64 s[52:53], -1, 0
	v_lshlrev_b64 v[4:5], 5, v[4:5]
	v_lshlrev_b64 v[6:7], 5, v[6:7]
	v_lshlrev_b64 v[8:9], 5, v[8:9]
	v_lshlrev_b64 v[10:11], 5, v[10:11]
	v_lshlrev_b64 v[14:15], 5, v[14:15]
	v_lshlrev_b64 v[16:17], 5, v[16:17]
	v_lshlrev_b64 v[18:19], 5, v[18:19]
	v_and_b32_e32 v12, 0xfc, v12
	v_bitop3_b32 v32, v20, s16, v21 bitop3:0x6c
	s_add_i32 s54, s28, 0xffffff80
	s_branch .LBB0_507

.Lfox_nock1:
	s_or_b64 exec, exec, s[12:13]
	global_load_dwordx4 v[118:121], v[248:249], off
	v_max3_f32 v125, v125, v54, v55
	v_max3_f32 v124, v124, v56, v57
	v_max3_f32 v125, v125, v58, v59
	v_mfma_f32_32x32x16_bf16 v[14:29], v[198:201], v[230:233], v[14:29]
	ds_read_b128 v[198:201], v218 offset:13344
	v_max3_f32 v124, v124, v60, v61
	v_max3_f32 v125, v125, v62, v63
	v_max3_f32 v124, v124, v64, v65
	v_mfma_f32_32x32x16_bf16 v[30:45], v[202:205], v[230:233], v[30:45]
	ds_read_b128 v[202:205], v218 offset:17952
	v_max3_f32 v125, v125, v66, v67
	v_max3_f32 v124, v124, v68, v69
	v_max3_f32 v125, v125, v70, v71
	v_mfma_f32_32x32x16_bf16 v[14:29], v[206:209], v[234:237], v[14:29]
	ds_read_b128 v[206:209], v218 offset:13376
	v_max3_f32 v124, v124, v72, v73
	v_max3_f32 v125, v125, v74, v75
	v_mfma_f32_32x32x16_bf16 v[30:45], v[210:213], v[234:237], v[30:45]
	ds_read_b128 v[210:213], v218 offset:17984
	v_max3_f32 v124, v124, v76, v77
	v_max_f32_e32 v124, v124, v125
	v_mfma_f32_32x32x16_bf16 v[14:29], v[214:217], v[238:241], v[14:29]
	ds_read_b128 v[214:217], v218 offset:13408
	v_mov_b32_e32 v125, v124
	s_nop 1
	v_mfma_f32_32x32x16_bf16 v[30:45], v[222:225], v[238:241], v[30:45]
	s_waitcnt lgkmcnt(14)
	ds_read_b128 v[222:225], v218 offset:18016
	v_permlane32_swap_b32_e32 v124, v125
	v_max_f32_e32 v126, v124, v125
	v_lshl_add_u64 v[244:245], v[244:245], 0, s[46:47]
	v_lshl_add_u64 v[248:249], v[248:249], 0, s[46:47]
	v_lshl_add_u64 v[250:251], v[250:251], 0, s[48:49]
	s_add_i32 s10, s10, 2
	s_add_i32 s12, s10, 2
	s_cmp_ge_i32 s12, s35
	s_cbranch_scc0 .Lfox_loop
	s_waitcnt vmcnt(0) lgkmcnt(0)
	s_branch .LBB0_670

.Lmla_nokr1:
	s_or_b64 exec, exec, s[4:5]
	v_add_f32_e32 v242, v242, v104
	v_add_f32_e32 v243, v243, v105
	v_add_f32_e32 v238, v238, v106
	v_add_f32_e32 v239, v239, v107
	v_add_f32_e32 v242, v242, v108
	v_add_f32_e32 v243, v243, v109
	v_add_f32_e32 v238, v238, v239
	v_mfma_f32_32x32x16_bf16 v[14:29], v[172:175], v[230:233], v[14:29]
	ds_read_b128 v[172:175], v162 offset:13376
	v_add_f32_e32 v242, v242, v243
	v_add_f32_e32 v238, v238, v242
	v_add_f32_e32 v165, v165, v238
	v_max3_f32 v240, v46, v47, v48
	v_max3_f32 v241, v49, v50, v51
	v_max3_f32 v240, v240, v52, v53
	v_mfma_f32_32x32x16_bf16 v[30:45], v[178:181], v[230:233], v[30:45]
	ds_read_b128 v[178:181], v162 offset:20032
	global_load_dwordx4 v[130:133], v227, s[54:55]
	s_add_u32 s54, s54, 0x10000
	s_addc_u32 s55, s55, 0
	s_add_u32 s56, s56, 0x1000
	s_addc_u32 s57, s57, 0
	v_max3_f32 v241, v241, v54, v55
	v_max3_f32 v240, v240, v56, v57
	v_max3_f32 v241, v241, v58, v59
	v_max3_f32 v240, v240, v60, v61
	v_max3_f32 v241, v241, v62, v63
	v_max3_f32 v240, v240, v64, v65
	v_mfma_f32_32x32x16_bf16 v[14:29], v[182:185], v[234:237], v[14:29]
	ds_read_b128 v[182:185], v162 offset:13408
	v_max3_f32 v241, v241, v66, v67
	v_max3_f32 v240, v240, v68, v69
	v_max3_f32 v241, v241, v70, v71
	v_max3_f32 v240, v240, v72, v73
	v_max3_f32 v241, v241, v74, v75
	v_mfma_f32_32x32x16_bf16 v[30:45], v[186:189], v[234:237], v[30:45]
	ds_read_b128 v[186:189], v162 offset:20064
	v_max3_f32 v240, v240, v76, v77
	v_max_f32_e32 v240, v240, v241
	v_mov_b32_e32 v241, v240
	s_nop 1
	v_permlane32_swap_b32_e32 v240, v241
	v_max_f32_e32 v244, v240, v241
	s_add_i32 s10, s10, 2
	s_add_i32 s4, s35, 2
	s_cmp_ge_u32 s10, s4
	s_cbranch_scc0 .Lmla_loop
	s_waitcnt vmcnt(0) lgkmcnt(0)
	v_add_f32_e32 v46, v46, v164
	v_add_f32_e32 v47, v47, v164
	v_add_f32_e32 v48, v48, v164
	v_add_f32_e32 v49, v49, v164
	v_add_f32_e32 v50, v50, v164
	v_add_f32_e32 v51, v51, v164
	v_add_f32_e32 v52, v52, v164
	v_add_f32_e32 v53, v53, v164
	v_add_f32_e32 v54, v54, v164
	v_add_f32_e32 v55, v55, v164
	v_add_f32_e32 v56, v56, v164
	v_add_f32_e32 v57, v57, v164
	v_add_f32_e32 v58, v58, v164
	v_add_f32_e32 v59, v59, v164
	v_add_f32_e32 v60, v60, v164
	v_add_f32_e32 v61, v61, v164
	v_add_f32_e32 v62, v62, v164
	v_add_f32_e32 v63, v63, v164
	v_add_f32_e32 v64, v64, v164
	v_add_f32_e32 v65, v65, v164
	v_add_f32_e32 v66, v66, v164
	v_add_f32_e32 v67, v67, v164
	v_add_f32_e32 v68, v68, v164
	v_add_f32_e32 v69, v69, v164
	v_add_f32_e32 v70, v70, v164
	v_add_f32_e32 v71, v71, v164
	v_add_f32_e32 v72, v72, v164
	v_add_f32_e32 v73, v73, v164
	v_add_f32_e32 v74, v74, v164
	v_add_f32_e32 v75, v75, v164
	v_add_f32_e32 v76, v76, v164
	v_add_f32_e32 v77, v77, v164
	s_branch .LBB0_738
